# attention phase start: all threads touch the parameter lines (no wait) so the serialized table-setup loads hit cache
# baseline (speedup 1.0000x reference)
; #define LAS __attribute__((address_space(3)))
; __device__ __forceinline__ void attn_setup(const float* par, int l, LAS unsigned char* lds) {
;     int tid_ = threadIdx.x; asm volatile("" : "+v"(tid_));
;     const int tid = tid_, lane = tid & 63, wave = tid >> 6;
;     LAS float* misc = (LAS float*)(lds + MISC_OFF);
;     const float* rb = par + P_RB;
;     if (wave == 0) {
;         const float mq = wave_max(lane < 32 ? fabsf(par[P_DQN + l * 32 + lane]) : 0.f), mk = wave_max(lane < 32 ? fabsf(par[P_DKN + l * 32 + lane]) : 0.f);
;         const float mlq = wave_max(fabsf(par[P_LQN + l * 64 + lane])), mlk = wave_max(fabsf(par[P_LKN + l * 64 + lane]));
.LBB0_447:
	s_or_b64 exec, exec, s[44:45]
	s_mov_b64 s[8:9], s[42:43]
	s_waitcnt lgkmcnt(0)
	s_barrier
	v_lshlrev_b32_e32 v236, 2, v154
	s_add_u32 s96, s42, 0xc2400
	s_addc_u32 s97, s43, 0
	global_load_dword v237, v236, s[96:97]
	global_load_dword v238, v236, s[96:97] offset:2048
	s_add_u32 s96, s42, 0xc5000
	s_addc_u32 s97, s43, 0
	global_load_dword v239, v236, s[96:97]
	s_add_u32 s46, s8, 0xc0000
	s_addc_u32 s47, s9, 0
	v_mov_b32_e32 v0, v154
	s_add_u32 s10, s8, 0xc5000
	s_addc_u32 s11, s9, 0
	v_cmp_gt_u32_e32 vcc, 64, v0
	s_and_saveexec_b64 s[12:13], vcc
	s_cbranch_execz .LBB0_500
	v_and_b32_e32 v13, 63, v0
	v_mov_b32_e32 v1, 0
	v_cmp_gt_u32_e64 s[2:3], 32, v13
	v_cmp_lt_u32_e32 vcc, 31, v13
	v_mov_b64_e32 v[2:3], v[0:1]
	s_and_saveexec_b64 s[6:7], vcc
	s_xor_b64 s[6:7], exec, s[6:7]
	v_mov_b32_e32 v3, 0
	v_mov_b32_e32 v2, v0
	s_andn2_saveexec_b64 s[6:7], s[6:7]
	s_cbranch_execz .LBB0_452
	v_lshl_add_u64 v[4:5], v[0:1], 2, s[46:47]
	v_add_co_u32_e32 v4, vcc, 0x2000, v4
	s_nop 1
	v_addc_co_u32_e32 v5, vcc, 0, v5, vcc
	flat_load_dword v1, v[4:5] offset:1024
	s_waitcnt vmcnt(0) lgkmcnt(0)
	v_and_b32_e32 v1, 0x7fffffff, v1

; #define LAS __attribute__((address_space(3)))
; __device__ __forceinline__ void attn_setup(const float* par, int l, LAS unsigned char* lds) {
;     int tid_ = threadIdx.x; asm volatile("" : "+v"(tid_));
;     const int tid = tid_, lane = tid & 63, wave = tid >> 6;
;     LAS float* misc = (LAS float*)(lds + MISC_OFF);
;     const float* rb = par + P_RB;
;     if (wave == 0) {
;         const float mq = wave_max(lane < 32 ? fabsf(par[P_DQN + l * 32 + lane]) : 0.f), mk = wave_max(lane < 32 ? fabsf(par[P_DKN + l * 32 + lane]) : 0.f);
;         const float mlq = wave_max(fabsf(par[P_LQN + l * 64 + lane])), mlk = wave_max(fabsf(par[P_LKN + l * 64 + lane]));
.LBB0_1161:
	s_or_b64 exec, exec, s[40:41]
	s_mov_b64 s[40:41], s[42:43]
	s_waitcnt lgkmcnt(0)
	s_barrier
	v_lshlrev_b32_e32 v236, 2, v154
	s_add_u32 s96, s42, 0xc2400
	s_addc_u32 s97, s43, 0
	global_load_dword v237, v236, s[96:97]
	global_load_dword v238, v236, s[96:97] offset:2048
	s_add_u32 s96, s42, 0xc5000
	s_addc_u32 s97, s43, 0
	global_load_dword v239, v236, s[96:97]
	v_mov_b32_e32 v0, v154
	s_add_u32 s10, s40, 0xc5000
	s_addc_u32 s11, s41, 0
	v_cmp_gt_u32_e32 vcc, 64, v0
	s_and_saveexec_b64 s[12:13], vcc
	s_cbranch_execz .LBB0_1212
	s_add_u32 s16, s40, 0xc0000
	v_and_b32_e32 v15, 63, v0
	s_addc_u32 s17, s41, 0
	v_cmp_gt_u32_e64 s[4:5], 32, v15
	v_mov_b32_e32 v4, 0
	v_or_b32_e32 v2, 32, v0
	v_mov_b32_e32 v1, 0
	s_and_saveexec_b64 s[8:9], s[4:5]
	s_cbranch_execz .LBB0_1164
	v_mov_b32_e32 v3, 0
	v_lshl_add_u64 v[6:7], v[2:3], 2, s[16:17]
	v_add_co_u32_e32 v6, vcc, 0x2000, v6
	s_nop 1
	v_addc_co_u32_e32 v7, vcc, 0, v7, vcc
	flat_load_dword v1, v[6:7] offset:1024
	s_waitcnt vmcnt(0) lgkmcnt(0)
	v_and_b32_e32 v1, 0x7fffffff, v1
